# baseline (speedup 1.0000x reference)
; DI_ unsigned pk2(float lo, float hi) { typedef float f2 __attribute__((ext_vector_type(2))); typedef __bf16 b2 __attribute__((ext_vector_type(2))); f2 v = {lo, hi}; b2 b = __builtin_convertvector(v, b2); return __builtin_bit_cast(unsigned, b); }
; #define MFMA32(a, b, c) __builtin_amdgcn_mfma_f32_32x32x16_bf16((a), (b), (c), 0, 0, 0)
; DI_ int crow(int r, int hi) { return (r & 3) + 8 * (r >> 2) + 4 * hi; }
; DI_ void ssd_passA(const bf16_t* xsT, const bf16_t* BT, const float* dt, const float* acum, bf16_t* Sc, unsigned char* lds, int tid, int lane, int wid) {
;     ...
;                 const bf16_t* bp = BT + (size_t)(g * 128 + 32 * nblk + r32) * XP + t0 + 8 * hi;
;                 f32x16 acc0;
; #pragma unroll
;                 for (int i = 0; i < 16; ++i) acc0[i] = 0.f;
; #pragma unroll
;                 for (int ks = 0; ks < 8; ++ks) acc0 = MFMA32(xa[ks], *(const bf16x8*)(bp + 16 * ks), acc0);
;                 bf16_t* so = Sc + ((size_t)(c * SHEADS + hA + h2) * 64 + 32 * pblk) * 128 + 32 * nblk + (r32 & ~1);
; #pragma unroll
;                 for (int k = 0; k < 8; ++k) {
;                     const float ve = acc0[2 * k], vo = acc0[2 * k + 1];
;                     const float send = (lane & 1) ? ve : vo, recv = __shfl_xor(send, 1);
;                     const unsigned w = (lane & 1) ? pk2(recv, vo) : pk2(ve, recv);
;                     *(unsigned*)(so + (size_t)crow(2 * k + (lane & 1), hi) * 128) = w;
;                 }
.Lmy_pa_join:
	global_load_dwordx4 v[206:209], v[234:235], off
	global_load_dwordx4 v[210:213], v[234:235], off offset:32
	global_load_dwordx4 v[214:217], v[234:235], off offset:64
	global_load_dwordx4 v[218:221], v[234:235], off offset:96
	global_load_dwordx4 v[222:225], v[234:235], off offset:128
	global_load_dwordx4 v[226:229], v[234:235], off offset:160
	global_load_dwordx4 v[236:239], v[234:235], off offset:192
	global_load_dwordx4 v[240:243], v[234:235], off offset:224
	s_nop 11
	v_cndmask_b32_e32 v230, v0, v1, vcc
	ds_bpermute_b32 v230, v70, v230
	v_cndmask_b32_e32 v231, v2, v3, vcc
	ds_bpermute_b32 v231, v70, v231
	v_cndmask_b32_e32 v232, v4, v5, vcc
	ds_bpermute_b32 v232, v70, v232
	v_cndmask_b32_e32 v233, v6, v7, vcc
	ds_bpermute_b32 v233, v70, v233
	v_cndmask_b32_e32 v246, v8, v9, vcc
	ds_bpermute_b32 v246, v70, v246
	v_cndmask_b32_e32 v247, v10, v11, vcc
	ds_bpermute_b32 v247, v70, v247
	v_cndmask_b32_e32 v248, v12, v13, vcc
	ds_bpermute_b32 v248, v70, v248
	v_cndmask_b32_e32 v249, v14, v15, vcc
	ds_bpermute_b32 v249, v70, v249
	s_waitcnt lgkmcnt(7)
	v_cndmask_b32_e32 v1, v1, v230, vcc
	v_cndmask_b32_e32 v0, v230, v0, vcc
	v_cvt_pk_bf16_f32 v68, v0, v1
	v_lshl_add_u64 v[0:1], v[62:63], 0, s[10:11]
	v_add_co_u32_e64 v66, s[0:1], s0, v0
	s_add_u32 s10, s10, 0x80
	s_nop 0
	v_addc_co_u32_e64 v67, s[0:1], 0, v1, s[0:1]
	s_mov_b32 s0, 0x1a201000
	s_nop 0
	v_add_co_u32_e64 v64, s[0:1], s0, v0
	s_nop 1
	v_addc_co_u32_e64 v65, s[0:1], 0, v1, s[0:1]
	global_store_dword v[64:65], v68, off offset:-4096
	s_addc_u32 s11, s11, 0
	s_waitcnt lgkmcnt(6)
	v_cndmask_b32_e32 v1, v3, v231, vcc
	v_cndmask_b32_e32 v0, v231, v2, vcc
	v_cvt_pk_bf16_f32 v0, v0, v1
	global_store_dword v[66:67], v0, off offset:512
	s_cmpk_eq_i32 s10, 0x100
	s_waitcnt lgkmcnt(5)
	v_cndmask_b32_e32 v1, v5, v232, vcc
	v_cndmask_b32_e32 v0, v232, v4, vcc
	v_cvt_pk_bf16_f32 v0, v0, v1
	global_store_dword v[66:67], v0, off offset:2048
	s_waitcnt lgkmcnt(4)
	v_cndmask_b32_e32 v1, v7, v233, vcc
	v_cndmask_b32_e32 v0, v233, v6, vcc
	v_cvt_pk_bf16_f32 v0, v0, v1
	global_store_dword v[66:67], v0, off offset:2560
	s_waitcnt lgkmcnt(3)
	v_cndmask_b32_e32 v1, v9, v246, vcc
	v_cndmask_b32_e32 v0, v246, v8, vcc
	v_cvt_pk_bf16_f32 v0, v0, v1
	global_store_dword v[64:65], v0, off
	s_waitcnt lgkmcnt(2)
	v_cndmask_b32_e32 v1, v11, v247, vcc
	v_cndmask_b32_e32 v0, v247, v10, vcc
	v_cvt_pk_bf16_f32 v0, v0, v1
	global_store_dword v[64:65], v0, off offset:512
	s_waitcnt lgkmcnt(1)
	v_cndmask_b32_e32 v1, v13, v248, vcc
	v_cndmask_b32_e32 v0, v248, v12, vcc
	v_cvt_pk_bf16_f32 v0, v0, v1
	global_store_dword v[64:65], v0, off offset:2048
	s_waitcnt lgkmcnt(0)
	v_cndmask_b32_e32 v1, v15, v249, vcc
	v_cndmask_b32_e32 v0, v249, v14, vcc
	v_cvt_pk_bf16_f32 v0, v0, v1
	global_store_dword v[64:65], v0, off offset:2560
	v_add_u32_e32 v80, 64, v80
	s_waitcnt vmcnt(15)
	v_mfma_f32_32x32x16_bf16 v[0:15], v[16:19], v[206:209], 0
	s_waitcnt vmcnt(14)
	v_mfma_f32_32x32x16_bf16 v[0:15], v[20:23], v[210:213], v[0:15]
	s_waitcnt vmcnt(13)
	v_mfma_f32_32x32x16_bf16 v[0:15], v[24:27], v[214:217], v[0:15]
	s_waitcnt vmcnt(12)
	v_mfma_f32_32x32x16_bf16 v[0:15], v[28:31], v[218:221], v[0:15]
	s_waitcnt vmcnt(11)
	v_mfma_f32_32x32x16_bf16 v[0:15], v[32:35], v[222:225], v[0:15]
	s_waitcnt vmcnt(10)
	v_mfma_f32_32x32x16_bf16 v[0:15], v[36:39], v[226:229], v[0:15]
	s_waitcnt vmcnt(9)
	v_mfma_f32_32x32x16_bf16 v[0:15], v[40:43], v[236:239], v[0:15]
	s_waitcnt vmcnt(8)
	v_mfma_f32_32x32x16_bf16 v[0:15], v[44:47], v[240:243], v[0:15]
	s_cbranch_scc1 .Lmy_pa_nopf
	global_load_dwordx4 v[206:209], v[244:245], off
	global_load_dwordx4 v[210:213], v[244:245], off offset:32
	global_load_dwordx4 v[214:217], v[244:245], off offset:64
	global_load_dwordx4 v[218:221], v[244:245], off offset:96
	global_load_dwordx4 v[222:225], v[244:245], off offset:128
	global_load_dwordx4 v[226:229], v[244:245], off offset:160
	global_load_dwordx4 v[236:239], v[244:245], off offset:192
	global_load_dwordx4 v[240:243], v[244:245], off offset:224
.Lmy_pa_nopf:
	s_nop 11
	v_cndmask_b32_e32 v230, v0, v1, vcc
	ds_bpermute_b32 v230, v70, v230
	v_cndmask_b32_e32 v231, v2, v3, vcc
	ds_bpermute_b32 v231, v70, v231
	v_cndmask_b32_e32 v232, v4, v5, vcc
	ds_bpermute_b32 v232, v70, v232
	v_cndmask_b32_e32 v233, v6, v7, vcc
	ds_bpermute_b32 v233, v70, v233
	v_cndmask_b32_e32 v246, v8, v9, vcc
	ds_bpermute_b32 v246, v70, v246
	v_cndmask_b32_e32 v247, v10, v11, vcc
	ds_bpermute_b32 v247, v70, v247
	v_cndmask_b32_e32 v248, v12, v13, vcc
	ds_bpermute_b32 v248, v70, v248
	v_cndmask_b32_e32 v249, v14, v15, vcc
	ds_bpermute_b32 v249, v70, v249
	s_waitcnt lgkmcnt(7)
	v_cndmask_b32_e32 v1, v1, v230, vcc
	v_cndmask_b32_e32 v0, v230, v0, vcc
	v_cvt_pk_bf16_f32 v0, v0, v1
	global_store_dword v[66:67], v0, off offset:64
	s_waitcnt lgkmcnt(6)
	v_cndmask_b32_e32 v1, v3, v231, vcc
	v_cndmask_b32_e32 v0, v231, v2, vcc
	v_cvt_pk_bf16_f32 v0, v0, v1
	global_store_dword v[66:67], v0, off offset:576
	s_waitcnt lgkmcnt(5)
	v_cndmask_b32_e32 v1, v5, v232, vcc
	v_cndmask_b32_e32 v0, v232, v4, vcc
	v_cvt_pk_bf16_f32 v0, v0, v1
	global_store_dword v[66:67], v0, off offset:2112
	s_waitcnt lgkmcnt(4)
	v_cndmask_b32_e32 v1, v7, v233, vcc
	v_cndmask_b32_e32 v0, v233, v6, vcc
	v_cvt_pk_bf16_f32 v0, v0, v1
	global_store_dword v[66:67], v0, off offset:2624
	s_waitcnt lgkmcnt(3)
	v_cndmask_b32_e32 v1, v9, v246, vcc
	v_cndmask_b32_e32 v0, v246, v8, vcc
	v_cvt_pk_bf16_f32 v0, v0, v1
	global_store_dword v[64:65], v0, off offset:64
	s_waitcnt lgkmcnt(2)
	v_cndmask_b32_e32 v1, v11, v247, vcc
	v_cndmask_b32_e32 v0, v247, v10, vcc
	v_cvt_pk_bf16_f32 v0, v0, v1
	global_store_dword v[64:65], v0, off offset:576
	s_waitcnt lgkmcnt(1)
	v_cndmask_b32_e32 v1, v13, v248, vcc
	v_cndmask_b32_e32 v0, v248, v12, vcc
	v_cvt_pk_bf16_f32 v0, v0, v1
	global_store_dword v[64:65], v0, off offset:2112
	s_waitcnt lgkmcnt(0)
	v_cndmask_b32_e32 v1, v15, v249, vcc
	v_cndmask_b32_e32 v0, v249, v14, vcc
	v_cvt_pk_bf16_f32 v0, v0, v1
	global_store_dword v[64:65], v0, off offset:2624
	s_cbranch_scc0 .LBB0_656
	s_add_i32 s27, s27, 1
	s_xor_b64 s[6:7], s[6:7], -1
	s_cmp_eq_u32 s27, 4
	s_cbranch_scc0 .LBB0_655
	v_readlane_b32 s0, v254, 6
	s_add_i32 s20, s20, s92
	s_add_i32 s19, s19, s0
	s_cmpk_gt_i32 s20, 0xff
	s_barrier
	s_cbranch_scc0 .LBB0_654
	v_readlane_b32 s26, v254, 36
	v_readlane_b32 s27, v254, 37
